# candidateA_plus_attention_prefetch_fast_path
# speedup vs baseline: 1.0052x; 1.0050x over previous
; template <int DK, bool BIAS> ...
;     ...
;   auto prefetch = [&](int j, uint4& rk0, uint4& rk1, uint4& rv, float& rfk) {
;     rk0 = kload(64 * j + krow0, kch0);
;     if (NPIECE > 512 && tid + 512 < NPIECE) rk1 = kload(64 * j + krow1, kch1);
;     { const int kg = 64 * j + vrow; rv = make_uint4(0, 0, 0, 0); if (kg < T) rv = *(const uint4*)(Vp + (size_t)(rowb + kg) * ldv + vch * 8); }
;     if (BIAS && tid < 64) { const int kg = 64 * j + tid; rfk = kg < T ? -fc[kg] * LOG2E : 0.f; }
;   };
;     ...
;   auto tile_step = [&](const int j, uint4& pk0, uint4& pk1, uint4& pv, float& pfk, const uint4& sk0, const uint4& sk1, const uint4& sv, const float& sfk) {
;     const int buf = j & 1;
;     if (j + 2 < nkv) prefetch(j + 2, pk0, pk1, pv, pfk);
.LBB0_1762:
	s_add_i32 s39, s37, -3
	s_cmp_lt_u32 s39, s21
	s_cselect_b64 s[92:93], -1, 0
	s_cmp_ge_u32 s39, s21
	s_cbranch_scc1 .LBB0_1772
	s_add_i32 s0, s38, 0xbf
	s_cmp_lt_i32 s0, s29
	s_cbranch_scc0 .Lpf_fox1_slow
	s_waitcnt vmcnt(0)
	v_add_u32_e32 v16, s38, v160
	v_add_u32_e32 v16, 0x80, v16
	v_mad_i64_i32 v[16:17], s[18:19], v16, s53, v[108:109]
	global_load_dwordx4 v[16:19], v[16:17], off
	v_add_u32_e32 v20, 0x48000, v172
	v_mov_b32_e32 v21, v130
	v_lshl_add_u64 v[20:21], v[20:21], 1, v[110:111]
	global_load_dwordx4 v[20:23], v[20:21], off
	s_and_saveexec_b64 s[0:1], s[6:7]
	s_cbranch_execz .Lpf_fox1_e
	v_add_u32_e32 v64, s38, v102
	v_add_u32_e32 v64, 0x80, v64
	v_ashrrev_i32_e32 v65, 31, v64
	v_lshl_add_u64 v[64:65], v[64:65], 2, s[16:17]
	global_load_dword v64, v[64:65], off
	s_waitcnt vmcnt(0)
	v_mul_f32_e32 v162, 0xbfb8aa3b, v64
.Lpf_fox1_e:
	s_or_b64 exec, exec, s[0:1]
	s_branch .LBB0_1772
.Lpf_fox1_slow:
	s_waitcnt vmcnt(0)
	v_add_u32_e32 v16, s38, v159
	v_add_u32_e32 v16, 0x80, v16
	v_mov_b32_e32 v20, 0
	v_mov_b32_e32 v21, v130
	v_cmp_gt_i32_e32 vcc, s29, v16
	v_mov_b64_e32 v[16:17], v[20:21]
	v_mov_b64_e32 v[18:19], v[20:21]
	s_and_saveexec_b64 s[0:1], vcc
	s_cbranch_execz .LBB0_1765
	v_add_u32_e32 v16, s38, v160
	v_add_u32_e32 v16, 0x80, v16
	v_mad_i64_i32 v[16:17], s[18:19], v16, s53, v[108:109]
	global_load_dwordx4 v[16:19], v[16:17], off

; template <int DK, bool BIAS> ...
;     ...
;   auto prefetch = [&](int j, uint4& rk0, uint4& rk1, uint4& rv, float& rfk) {
;     rk0 = kload(64 * j + krow0, kch0);
;     if (NPIECE > 512 && tid + 512 < NPIECE) rk1 = kload(64 * j + krow1, kch1);
;     { const int kg = 64 * j + vrow; rv = make_uint4(0, 0, 0, 0); if (kg < T) rv = *(const uint4*)(Vp + (size_t)(rowb + kg) * ldv + vch * 8); }
;     if (BIAS && tid < 64) { const int kg = 64 * j + tid; rfk = kg < T ? -fc[kg] * LOG2E : 0.f; }
;   };
;     ...
;   auto tile_step = [&](const int j, uint4& pk0, uint4& pk1, uint4& pv, float& pfk, const uint4& sk0, const uint4& sk1, const uint4& sv, const float& sfk) {
;     const int buf = j & 1;
;     if (j + 2 < nkv) prefetch(j + 2, pk0, pk1, pv, pfk);
.LBB0_1782:
	s_waitcnt lgkmcnt(0)
	s_barrier
	s_and_b64 vcc, exec, s[0:1]
	s_cbranch_vccnz .LBB0_1761
	s_cmp_gt_u32 s37, s21
	s_cbranch_scc1 .LBB0_1793
	s_add_i32 s0, s38, 0xff
	s_cmp_lt_i32 s0, s29
	s_cbranch_scc0 .Lpf_fox2_slow
	s_waitcnt vmcnt(0)
	v_add_u32_e32 v24, s38, v160
	v_add_u32_e32 v24, 0xc0, v24
	v_mad_i64_i32 v[24:25], s[18:19], v24, s53, v[108:109]
	global_load_dwordx4 v[24:27], v[24:25], off
	v_add_u32_e32 v28, 0x6c000, v172
	v_mov_b32_e32 v29, v130
	v_lshl_add_u64 v[28:29], v[28:29], 1, v[110:111]
	global_load_dwordx4 v[28:31], v[28:29], off
	s_and_saveexec_b64 s[0:1], s[6:7]
	s_cbranch_execz .Lpf_fox2_e
	v_add_u32_e32 v64, s38, v102
	v_add_u32_e32 v64, 0xc0, v64
	v_ashrrev_i32_e32 v65, 31, v64
	v_lshl_add_u64 v[64:65], v[64:65], 2, s[16:17]
	global_load_dword v64, v[64:65], off
	s_waitcnt vmcnt(0)
	v_mul_f32_e32 v166, 0xbfb8aa3b, v64

; template <int DK, bool BIAS> ...
;     ...
;   auto kload = [&](int kg, int chn) -> uint4 {
;     uint4 u = make_uint4(0, 0, 0, 0);
;     if (kg < T) { if (DK == 64 || chn < 8) u = *(const uint4*)(Kp + (size_t)(rowb + kg) * ldk + chn * 8); else u = *(const uint4*)(K2p + (size_t)(rowb + kg) * ldk2 + (chn - 8) * 8); }
;     return u; };
;   auto prefetch = [&](int j, uint4& rk0, uint4& rk1, uint4& rv, float& rfk) {
;     rk0 = kload(64 * j + krow0, kch0);
;     if (NPIECE > 512 && tid + 512 < NPIECE) rk1 = kload(64 * j + krow1, kch1);
;     { const int kg = 64 * j + vrow; rv = make_uint4(0, 0, 0, 0); if (kg < T) rv = *(const uint4*)(Vp + (size_t)(rowb + kg) * ldv + vch * 8); }
.Lpf_fox2_slow:
	s_waitcnt vmcnt(1)
	v_add_u32_e32 v24, s38, v159
	v_add_u32_e32 v24, 0xc0, v24
	s_waitcnt vmcnt(0)
	v_mov_b32_e32 v28, 0
	v_mov_b32_e32 v29, v130
	v_cmp_gt_i32_e32 vcc, s29, v24
	v_mov_b64_e32 v[24:25], v[28:29]
	v_mov_b64_e32 v[26:27], v[28:29]
	s_and_saveexec_b64 s[0:1], vcc
	s_cbranch_execz .LBB0_1786
	v_add_u32_e32 v24, s38, v160
	v_add_u32_e32 v24, 0xc0, v24
	v_mad_i64_i32 v[24:25], s[18:19], v24, s53, v[108:109]
	global_load_dwordx4 v[24:27], v[24:25], off

; template <int DK, bool BIAS> ...
;     ...
;   auto kload = [&](int kg, int chn) -> uint4 {
;     uint4 u = make_uint4(0, 0, 0, 0);
;     if (kg < T) { if (DK == 64 || chn < 8) u = *(const uint4*)(Kp + (size_t)(rowb + kg) * ldk + chn * 8); else u = *(const uint4*)(K2p + (size_t)(rowb + kg) * ldk2 + (chn - 8) * 8); }
;     return u; };
;   auto prefetch = [&](int j, uint4& rk0, uint4& rk1, uint4& rv, float& rfk) {
;     rk0 = kload(64 * j + krow0, kch0);
;     if (NPIECE > 512 && tid + 512 < NPIECE) rk1 = kload(64 * j + krow1, kch1);
;     { const int kg = 64 * j + vrow; rv = make_uint4(0, 0, 0, 0); if (kg < T) rv = *(const uint4*)(Vp + (size_t)(rowb + kg) * ldv + vch * 8); }
;     if (BIAS && tid < 64) { const int kg = 64 * j + tid; rfk = kg < T ? -fc[kg] * LOG2E : 0.f; }
;   };
.LBB0_1852:
	s_add_i32 s42, s43, -3
	s_cmp_lt_u32 s42, s21
	s_cselect_b64 s[16:17], -1, 0
	s_cmp_ge_u32 s42, s21
	s_cbranch_scc1 .LBB0_1862
	s_add_i32 s0, s58, 0xbf
	s_cmp_lt_i32 s0, s29
	s_cbranch_scc0 .Lpf_mla1_slow
	s_waitcnt vmcnt(0)
	v_mov_b32_e32 v131, v130
	v_add_u32_e32 v24, s58, v116
	v_add_u32_e32 v24, 0x80, v24
	v_ashrrev_i32_e32 v25, 31, v24
	v_lshlrev_b64 v[26:27], 11, v[24:25]
	v_lshlrev_b64 v[24:25], 6, v[24:25]
	v_lshl_add_u64 v[24:25], v[124:125], 0, v[24:25]
	v_lshl_add_u64 v[26:27], v[122:123], 0, v[26:27]
	v_lshl_add_u64 v[24:25], v[24:25], 0, s[48:49]
	v_cndmask_b32_e64 v25, v25, v27, s[10:11]
	v_cndmask_b32_e64 v24, v24, v26, s[10:11]
	global_load_dwordx4 v[24:27], v[24:25], off
	s_and_saveexec_b64 s[0:1], s[6:7]
	s_cbranch_execz .Lpf_mla1_e
	v_add_u32_e32 v28, s58, v118
	v_add_u32_e32 v28, 0x80, v28
	v_ashrrev_i32_e32 v29, 31, v28
	v_lshlrev_b64 v[28:29], v152, v[28:29]
	v_lshl_add_u64 v[28:29], v[150:151], 0, v[28:29]
	global_load_dwordx4 v[28:31], v[28:29], off
.Lpf_mla1_e:
	s_or_b64 exec, exec, s[0:1]
	v_add_u32_e32 v32, 0x20000, v207
	v_mov_b32_e32 v33, v130
	v_lshl_add_u64 v[32:33], v[32:33], 1, v[126:127]
	global_load_dwordx4 v[32:35], v[32:33], off offset:128
	s_branch .LBB0_1862
.Lpf_mla1_slow:
	s_waitcnt vmcnt(0)
	v_add_u32_e32 v24, s58, v196
	v_add_u32_e32 v24, 0x80, v24
	v_mov_b32_e32 v131, v130
	v_cmp_gt_i32_e32 vcc, s29, v24
	v_mov_b64_e32 v[24:25], v[130:131]
	v_mov_b64_e32 v[26:27], v[130:131]
	s_and_saveexec_b64 s[0:1], vcc
	s_cbranch_execz .LBB0_1855
	v_add_u32_e32 v24, s58, v116
	v_add_u32_e32 v24, 0x80, v24
	v_ashrrev_i32_e32 v25, 31, v24
	v_lshlrev_b64 v[26:27], 11, v[24:25]
	v_lshlrev_b64 v[24:25], 6, v[24:25]
	v_lshl_add_u64 v[24:25], v[124:125], 0, v[24:25]
	v_lshl_add_u64 v[26:27], v[122:123], 0, v[26:27]
	v_lshl_add_u64 v[24:25], v[24:25], 0, s[48:49]
	v_cndmask_b32_e64 v25, v25, v27, s[10:11]
	v_cndmask_b32_e64 v24, v24, v26, s[10:11]
	global_load_dwordx4 v[24:27], v[24:25], off

; template <int DK, bool BIAS> ...
;     ...
;   auto kload = [&](int kg, int chn) -> uint4 {
;     uint4 u = make_uint4(0, 0, 0, 0);
;     if (kg < T) { if (DK == 64 || chn < 8) u = *(const uint4*)(Kp + (size_t)(rowb + kg) * ldk + chn * 8); else u = *(const uint4*)(K2p + (size_t)(rowb + kg) * ldk2 + (chn - 8) * 8); }
;     return u; };
;   auto prefetch = [&](int j, uint4& rk0, uint4& rk1, uint4& rv, float& rfk) {
;     rk0 = kload(64 * j + krow0, kch0);
;     if (NPIECE > 512 && tid + 512 < NPIECE) rk1 = kload(64 * j + krow1, kch1);
;     { const int kg = 64 * j + vrow; rv = make_uint4(0, 0, 0, 0); if (kg < T) rv = *(const uint4*)(Vp + (size_t)(rowb + kg) * ldv + vch * 8); }
;     if (BIAS && tid < 64) { const int kg = 64 * j + tid; rfk = kg < T ? -fc[kg] * LOG2E : 0.f; }
;   };
.LBB0_1872:
	s_waitcnt lgkmcnt(0)
	s_barrier
	s_and_b64 vcc, exec, s[0:1]
	s_cbranch_vccnz .LBB0_1851
	s_cmp_gt_u32 s43, s21
	s_cbranch_scc1 .LBB0_1884
	s_add_i32 s0, s58, 0xff
	s_cmp_lt_i32 s0, s29
	s_cbranch_scc0 .Lpf_mla2_slow
	s_waitcnt vmcnt(0)
	v_mov_b32_e32 v131, v130
	v_add_u32_e32 v36, s58, v116
	v_add_u32_e32 v36, 0xc0, v36
	v_ashrrev_i32_e32 v37, 31, v36
	v_lshlrev_b64 v[38:39], 11, v[36:37]
	v_lshlrev_b64 v[36:37], 6, v[36:37]
	v_lshl_add_u64 v[36:37], v[124:125], 0, v[36:37]
	v_lshl_add_u64 v[38:39], v[122:123], 0, v[38:39]
	v_lshl_add_u64 v[36:37], v[36:37], 0, s[48:49]
	v_cndmask_b32_e64 v37, v37, v39, s[10:11]
	v_cndmask_b32_e64 v36, v36, v38, s[10:11]
	global_load_dwordx4 v[36:39], v[36:37], off
	s_and_saveexec_b64 s[0:1], s[6:7]
	s_cbranch_execz .Lpf_mla2_e
	v_add_u32_e32 v40, s58, v118
	v_add_u32_e32 v40, 0xc0, v40
	v_ashrrev_i32_e32 v41, 31, v40
	v_lshlrev_b64 v[40:41], v152, v[40:41]
	v_lshl_add_u64 v[40:41], v[150:151], 0, v[40:41]
	global_load_dwordx4 v[40:43], v[40:41], off
.Lpf_mla2_e:
	s_or_b64 exec, exec, s[0:1]
	v_add_u32_e32 v44, 0x30000, v207
	v_mov_b32_e32 v45, v130
	v_lshl_add_u64 v[44:45], v[44:45], 1, v[126:127]
	global_load_dwordx4 v[44:47], v[44:45], off offset:128
	s_branch .LBB0_1884
.Lpf_mla2_slow:
	s_waitcnt vmcnt(1)
	v_add_u32_e32 v36, s58, v196
	v_add_u32_e32 v36, 0xc0, v36
	v_mov_b32_e32 v131, v130
	v_cmp_gt_i32_e32 vcc, s29, v36
	v_mov_b64_e32 v[36:37], v[130:131]
	v_mov_b64_e32 v[38:39], v[130:131]
	s_and_saveexec_b64 s[0:1], vcc
	s_cbranch_execz .LBB0_1876
	v_add_u32_e32 v36, s58, v116
	v_add_u32_e32 v36, 0xc0, v36
	v_ashrrev_i32_e32 v37, 31, v36
	v_lshlrev_b64 v[38:39], 11, v[36:37]
	v_lshlrev_b64 v[36:37], 6, v[36:37]
	v_lshl_add_u64 v[36:37], v[124:125], 0, v[36:37]
	v_lshl_add_u64 v[38:39], v[122:123], 0, v[38:39]
	v_lshl_add_u64 v[36:37], v[36:37], 0, s[48:49]
	v_cndmask_b32_e64 v37, v37, v39, s[10:11]
	v_cndmask_b32_e64 v36, v36, v38, s[10:11]
	global_load_dwordx4 v[36:39], v[36:37], off
